# plus: relu-squared epilogue without the redundant canonicalising v_max (two nops after each store keep the store-data distance)
# speedup vs baseline: 1.0043x; 1.0043x over previous
; __device__ __forceinline__ unsigned cvt_pk_bf16(float lo, float hi) { f32x2 v = {lo, hi}; bf16x2_t r = __builtin_convertvector(v, bf16x2_t); return __builtin_bit_cast(unsigned, r); }
;     __device__ __forceinline__ void operator()(const f32x4 (&acc)[2][2][4][2], const pg8::Unit& u, int wr, int wc, int fr, int fq) const {
;         const int row0 = u.pm * 256 + wr * 64 + fr, col0 = u.pn * 256 + wc * 32 + 8 * fq;
; #pragma unroll
;         for (int ai = 0; ai < 2; ++ai)
; #pragma unroll
;             for (int m = 0; m < 4; ++m) { bf16_t* rowp = O + (size_t)(row0 + ai * 128 + m * 16) * DFF + col0;
; #pragma unroll
;                 for (int bj = 0; bj < 2; ++bj) { f32x4 v0 = acc[ai][bj][m][0], v1 = acc[ai][bj][m][1];
; #pragma unroll
;                     for (int j = 0; j < 4; ++j) { const float a = fmaxf(v0[j], 0.f), b = fmaxf(v1[j], 0.f); v0[j] = a * a; v1[j] = b * b; }
;                     u32x4 w; w.x = cvt_pk_bf16(v0[0], v0[1]); w.y = cvt_pk_bf16(v0[2], v0[3]); w.z = cvt_pk_bf16(v1[0], v1[1]); w.w = cvt_pk_bf16(v1[2], v1[3]);
;                     *(u32x4*)(rowp + bj * 128) = w; } }
;     }
.LBB0_37:
	v_lshl_add_u32 v146, s44, 8, v142
	v_lshl_or_b32 v140, s20, 8, v144
	v_ashrrev_i32_e32 v147, 31, v146
	v_ashrrev_i32_e32 v141, 31, v140
	v_lshlrev_b64 v[148:149], 14, v[146:147]
	v_lshl_add_u64 v[148:149], s[10:11], 0, v[148:149]
	v_lshlrev_b64 v[150:151], 1, v[140:141]
	v_max_f32_e32 v122, 0, v122
	v_max_f32_e32 v123, 0, v123
	v_lshl_add_u64 v[140:141], v[148:149], 0, v[150:151]
	v_pk_mul_f32 v[148:149], v[122:123], v[122:123]
	v_max_f32_e32 v124, 0, v124
	v_max_f32_e32 v126, 0, v126
	v_max_f32_e32 v127, 0, v127
	v_max_f32_e32 v122, 0, v128
	v_max_f32_e32 v123, 0, v129
	v_max_f32_e32 v125, 0, v125
	v_pk_mul_f32 v[126:127], v[126:127], v[126:127]
	v_pk_mul_f32 v[128:129], v[122:123], v[122:123]
	v_pk_mul_f32 v[152:153], v[124:125], v[124:125]
	v_cvt_pk_bf16_f32 v122, v126, v127
	v_cvt_pk_bf16_f32 v123, v128, v129
	v_cvt_pk_bf16_f32 v124, v148, v149
	v_cvt_pk_bf16_f32 v125, v152, v153
	v_max_f32_e32 v114, 0, v114
	v_max_f32_e32 v115, 0, v115
	global_store_dwordx4 v[140:141], v[122:125], off
	s_nop 1
	v_pk_mul_f32 v[122:123], v[114:115], v[114:115]
	v_max_f32_e32 v116, 0, v116
	v_max_f32_e32 v118, 0, v118
	v_max_f32_e32 v119, 0, v119
	v_max_f32_e32 v114, 0, v120
	v_max_f32_e32 v115, 0, v121
	v_max_f32_e32 v117, 0, v117
	v_pk_mul_f32 v[118:119], v[118:119], v[118:119]
	v_pk_mul_f32 v[120:121], v[114:115], v[114:115]
	v_pk_mul_f32 v[124:125], v[116:117], v[116:117]
	v_cvt_pk_bf16_f32 v114, v118, v119
	v_cvt_pk_bf16_f32 v115, v120, v121
	v_cvt_pk_bf16_f32 v116, v122, v123
	v_cvt_pk_bf16_f32 v117, v124, v125
	v_max_f32_e32 v106, 0, v106
	v_max_f32_e32 v107, 0, v107
	global_store_dwordx4 v[140:141], v[114:117], off offset:256
	s_nop 1
	v_or_b32_e32 v114, 16, v146
	v_pk_mul_f32 v[116:117], v[106:107], v[106:107]
	v_ashrrev_i32_e32 v115, 31, v114
	v_max_f32_e32 v108, 0, v108
	v_lshlrev_b64 v[114:115], 14, v[114:115]
	v_max_f32_e32 v110, 0, v110
	v_max_f32_e32 v111, 0, v111
	v_max_f32_e32 v106, 0, v112
	v_max_f32_e32 v107, 0, v113
	v_max_f32_e32 v109, 0, v109
	v_lshl_add_u64 v[114:115], s[10:11], 0, v[114:115]
	v_pk_mul_f32 v[110:111], v[110:111], v[110:111]
	v_pk_mul_f32 v[112:113], v[106:107], v[106:107]
	v_pk_mul_f32 v[118:119], v[108:109], v[108:109]
	v_lshl_add_u64 v[114:115], v[114:115], 0, v[150:151]
	v_cvt_pk_bf16_f32 v106, v110, v111
	v_cvt_pk_bf16_f32 v107, v112, v113
	v_cvt_pk_bf16_f32 v108, v116, v117
	v_cvt_pk_bf16_f32 v109, v118, v119
	v_max_f32_e32 v98, 0, v98
	v_max_f32_e32 v99, 0, v99
	global_store_dwordx4 v[114:115], v[106:109], off
	s_nop 1
	v_pk_mul_f32 v[106:107], v[98:99], v[98:99]
	v_max_f32_e32 v100, 0, v100
	v_max_f32_e32 v102, 0, v102
	v_max_f32_e32 v103, 0, v103
	v_max_f32_e32 v98, 0, v104
	v_max_f32_e32 v99, 0, v105
	v_max_f32_e32 v101, 0, v101
	v_pk_mul_f32 v[102:103], v[102:103], v[102:103]
	v_pk_mul_f32 v[104:105], v[98:99], v[98:99]
	v_pk_mul_f32 v[108:109], v[100:101], v[100:101]
	v_cvt_pk_bf16_f32 v98, v102, v103
	v_cvt_pk_bf16_f32 v99, v104, v105
	v_cvt_pk_bf16_f32 v100, v106, v107
	v_cvt_pk_bf16_f32 v101, v108, v109
	v_max_f32_e32 v90, 0, v90
	v_max_f32_e32 v91, 0, v91
	global_store_dwordx4 v[114:115], v[98:101], off offset:256
	s_nop 1
	v_or_b32_e32 v98, 32, v146
	v_pk_mul_f32 v[100:101], v[90:91], v[90:91]
	v_ashrrev_i32_e32 v99, 31, v98
	v_max_f32_e32 v92, 0, v92
	v_lshlrev_b64 v[98:99], 14, v[98:99]
	v_max_f32_e32 v94, 0, v94
	v_max_f32_e32 v95, 0, v95
	v_max_f32_e32 v90, 0, v96
	v_max_f32_e32 v91, 0, v97
	v_max_f32_e32 v93, 0, v93
	v_lshl_add_u64 v[98:99], s[10:11], 0, v[98:99]
	v_pk_mul_f32 v[94:95], v[94:95], v[94:95]
	v_pk_mul_f32 v[96:97], v[90:91], v[90:91]
	v_pk_mul_f32 v[102:103], v[92:93], v[92:93]
	v_lshl_add_u64 v[98:99], v[98:99], 0, v[150:151]
	v_cvt_pk_bf16_f32 v90, v94, v95
	v_cvt_pk_bf16_f32 v91, v96, v97
	v_cvt_pk_bf16_f32 v92, v100, v101
	v_cvt_pk_bf16_f32 v93, v102, v103
	v_max_f32_e32 v82, 0, v82
	v_max_f32_e32 v83, 0, v83
	global_store_dwordx4 v[98:99], v[90:93], off
	s_nop 1
	v_pk_mul_f32 v[90:91], v[82:83], v[82:83]
	v_max_f32_e32 v84, 0, v84
	v_max_f32_e32 v86, 0, v86
	v_max_f32_e32 v87, 0, v87
	v_max_f32_e32 v82, 0, v88
	v_max_f32_e32 v83, 0, v89
	v_max_f32_e32 v85, 0, v85
	v_pk_mul_f32 v[86:87], v[86:87], v[86:87]
	v_pk_mul_f32 v[88:89], v[82:83], v[82:83]
	v_pk_mul_f32 v[92:93], v[84:85], v[84:85]
	v_cvt_pk_bf16_f32 v82, v86, v87
	v_cvt_pk_bf16_f32 v83, v88, v89
	v_cvt_pk_bf16_f32 v84, v90, v91
	v_cvt_pk_bf16_f32 v85, v92, v93
	v_max_f32_e32 v74, 0, v74
	v_max_f32_e32 v75, 0, v75
	global_store_dwordx4 v[98:99], v[82:85], off offset:256
	s_nop 1
	v_or_b32_e32 v82, 48, v146
	v_pk_mul_f32 v[84:85], v[74:75], v[74:75]
	v_ashrrev_i32_e32 v83, 31, v82
	v_max_f32_e32 v76, 0, v76
	v_lshlrev_b64 v[82:83], 14, v[82:83]
	v_max_f32_e32 v78, 0, v78
	v_max_f32_e32 v79, 0, v79
	v_max_f32_e32 v74, 0, v80
	v_max_f32_e32 v75, 0, v81
	v_max_f32_e32 v77, 0, v77
	v_lshl_add_u64 v[82:83], s[10:11], 0, v[82:83]
	v_pk_mul_f32 v[78:79], v[78:79], v[78:79]
	v_pk_mul_f32 v[80:81], v[74:75], v[74:75]
	v_pk_mul_f32 v[86:87], v[76:77], v[76:77]
	v_lshl_add_u64 v[82:83], v[82:83], 0, v[150:151]
	v_cvt_pk_bf16_f32 v74, v78, v79
	v_cvt_pk_bf16_f32 v75, v80, v81
	v_cvt_pk_bf16_f32 v76, v84, v85
	v_cvt_pk_bf16_f32 v77, v86, v87
	v_max_f32_e32 v66, 0, v66
	v_max_f32_e32 v67, 0, v67
	global_store_dwordx4 v[82:83], v[74:77], off
	s_nop 1
	v_pk_mul_f32 v[74:75], v[66:67], v[66:67]
	v_max_f32_e32 v68, 0, v68
	v_max_f32_e32 v70, 0, v70
	v_max_f32_e32 v71, 0, v71
	v_max_f32_e32 v66, 0, v72
	v_max_f32_e32 v67, 0, v73
	v_max_f32_e32 v69, 0, v69
	v_pk_mul_f32 v[70:71], v[70:71], v[70:71]
	v_pk_mul_f32 v[72:73], v[66:67], v[66:67]
	v_pk_mul_f32 v[76:77], v[68:69], v[68:69]
	v_cvt_pk_bf16_f32 v66, v70, v71
; __device__ __forceinline__ unsigned cvt_pk_bf16(float lo, float hi) { f32x2 v = {lo, hi}; bf16x2_t r = __builtin_convertvector(v, bf16x2_t); return __builtin_bit_cast(unsigned, r); }
; #define PG8_BAR __builtin_amdgcn_s_barrier()
; template <class Epi, class Sched, bool ALIGN_EPI = false, bool SP2 = false>
; __device__ __forceinline__ void gemm_phase(LAS unsigned char* lds, const Gemm g, const Sched& S, const Epi& E, const int tid_) {
;     ...
;         E(acc, cur, wr, wc, fr, fq); S.done(cur);
;         if (!has_next) break;
; #pragma unroll
;         for (int a = 0; a < 2; ++a)
; #pragma unroll
;             for (int b = 0; b < 2; ++b)
; #pragma unroll
;                 for (int m = 0; m < 4; ++m)
; #pragma unroll
;                     for (int n = 0; n < 2; ++n) acc[a][b][m][n] = (f32x4){0.f, 0.f, 0.f, 0.f};
;         cur = nxt; cA = nA; cB = nB; ++ui;
;         if constexpr (ALIGN_EPI) { if (wr == 1) PG8_BAR; }
;     }
;     __device__ __forceinline__ void operator()(const f32x4 (&acc)[2][2][4][2], const pg8::Unit& u, int wr, int wc, int fr, int fq) const {
;     ...
;             for (int m = 0; m < 4; ++m) { bf16_t* rowp = O + (size_t)(row0 + ai * 128 + m * 16) * DFF + col0;
; #pragma unroll
;                 for (int bj = 0; bj < 2; ++bj) { f32x4 v0 = acc[ai][bj][m][0], v1 = acc[ai][bj][m][1];
; #pragma unroll
;                     for (int j = 0; j < 4; ++j) { const float a = fmaxf(v0[j], 0.f), b = fmaxf(v1[j], 0.f); v0[j] = a * a; v1[j] = b * b; }
;                     u32x4 w; w.x = cvt_pk_bf16(v0[0], v0[1]); w.y = cvt_pk_bf16(v0[2], v0[3]); w.z = cvt_pk_bf16(v1[0], v1[1]); w.w = cvt_pk_bf16(v1[2], v1[3]);
;                     *(u32x4*)(rowp + bj * 128) = w; } }
	v_cvt_pk_bf16_f32 v67, v72, v73
	v_cvt_pk_bf16_f32 v68, v74, v75
	v_cvt_pk_bf16_f32 v69, v76, v77
	v_max_f32_e32 v58, 0, v58
	v_max_f32_e32 v59, 0, v59
	global_store_dwordx4 v[82:83], v[66:69], off offset:256
	s_nop 1
	v_pk_mul_f32 v[68:69], v[58:59], v[58:59]
	v_max_f32_e32 v62, 0, v62
	v_max_f32_e32 v63, 0, v63
	v_max_f32_e32 v60, 0, v60
	v_pk_mul_f32 v[62:63], v[62:63], v[62:63]
	v_max_f32_e32 v58, 0, v64
	v_max_f32_e32 v59, 0, v65
	v_max_f32_e32 v61, 0, v61
	s_mov_b32 s15, 0x200000
	v_pk_mul_f32 v[64:65], v[58:59], v[58:59]
	v_pk_mul_f32 v[70:71], v[60:61], v[60:61]
	v_cvt_pk_bf16_f32 v58, v62, v63
	v_add_co_u32_e32 v62, vcc, s15, v140
	v_cvt_pk_bf16_f32 v59, v64, v65
	v_cvt_pk_bf16_f32 v60, v68, v69
	v_cvt_pk_bf16_f32 v61, v70, v71
	v_addc_co_u32_e32 v63, vcc, 0, v141, vcc
	v_max_f32_e32 v50, 0, v50
	v_max_f32_e32 v51, 0, v51
	global_store_dwordx4 v[62:63], v[58:61], off
	s_nop 1
	v_pk_mul_f32 v[58:59], v[50:51], v[50:51]
	v_max_f32_e32 v52, 0, v52
	v_max_f32_e32 v54, 0, v54
	v_max_f32_e32 v55, 0, v55
	v_max_f32_e32 v50, 0, v56
	v_max_f32_e32 v51, 0, v57
	v_max_f32_e32 v53, 0, v53
	s_mov_b64 s[20:21], 0x200000
	v_pk_mul_f32 v[54:55], v[54:55], v[54:55]
	v_pk_mul_f32 v[56:57], v[50:51], v[50:51]
	v_pk_mul_f32 v[60:61], v[52:53], v[52:53]
	v_lshl_add_u64 v[66:67], v[140:141], 0, s[20:21]
	v_cvt_pk_bf16_f32 v50, v54, v55
	v_cvt_pk_bf16_f32 v51, v56, v57
	v_cvt_pk_bf16_f32 v52, v58, v59
	v_cvt_pk_bf16_f32 v53, v60, v61
	v_max_f32_e32 v42, 0, v42
	v_max_f32_e32 v43, 0, v43
	global_store_dwordx4 v[66:67], v[50:53], off offset:256
	s_nop 1
	v_pk_mul_f32 v[52:53], v[42:43], v[42:43]
	v_max_f32_e32 v46, 0, v46
	v_max_f32_e32 v47, 0, v47
	v_max_f32_e32 v44, 0, v44
	v_pk_mul_f32 v[46:47], v[46:47], v[46:47]
	v_max_f32_e32 v42, 0, v48
	v_max_f32_e32 v43, 0, v49
	v_max_f32_e32 v45, 0, v45
	s_mov_b32 s15, 0x240000
	v_pk_mul_f32 v[48:49], v[42:43], v[42:43]
	v_pk_mul_f32 v[54:55], v[44:45], v[44:45]
	v_cvt_pk_bf16_f32 v42, v46, v47
	v_add_co_u32_e32 v46, vcc, s15, v140
	v_cvt_pk_bf16_f32 v43, v48, v49
	v_cvt_pk_bf16_f32 v44, v52, v53
	v_cvt_pk_bf16_f32 v45, v54, v55
	v_addc_co_u32_e32 v47, vcc, 0, v141, vcc
	v_max_f32_e32 v34, 0, v34
	v_max_f32_e32 v35, 0, v35
	global_store_dwordx4 v[46:47], v[42:45], off
	s_nop 1
	v_pk_mul_f32 v[42:43], v[34:35], v[34:35]
	v_max_f32_e32 v36, 0, v36
	v_max_f32_e32 v38, 0, v38
	v_max_f32_e32 v39, 0, v39
	v_max_f32_e32 v34, 0, v40
	v_max_f32_e32 v35, 0, v41
	v_max_f32_e32 v37, 0, v37
	s_mov_b64 s[20:21], 0x240000
	v_pk_mul_f32 v[38:39], v[38:39], v[38:39]
	v_pk_mul_f32 v[40:41], v[34:35], v[34:35]
	v_pk_mul_f32 v[44:45], v[36:37], v[36:37]
	v_lshl_add_u64 v[50:51], v[140:141], 0, s[20:21]
	v_cvt_pk_bf16_f32 v34, v38, v39
	v_cvt_pk_bf16_f32 v35, v40, v41
	v_cvt_pk_bf16_f32 v36, v42, v43
	v_cvt_pk_bf16_f32 v37, v44, v45
	v_max_f32_e32 v26, 0, v26
	v_max_f32_e32 v27, 0, v27
	global_store_dwordx4 v[50:51], v[34:37], off offset:256
	s_nop 1
	v_pk_mul_f32 v[36:37], v[26:27], v[26:27]
	v_max_f32_e32 v30, 0, v30
	v_max_f32_e32 v31, 0, v31
	v_max_f32_e32 v28, 0, v28
	v_pk_mul_f32 v[30:31], v[30:31], v[30:31]
	v_max_f32_e32 v26, 0, v32
	v_max_f32_e32 v27, 0, v33
	v_max_f32_e32 v29, 0, v29
	s_mov_b32 s15, 0x280000
	v_pk_mul_f32 v[32:33], v[26:27], v[26:27]
	v_pk_mul_f32 v[38:39], v[28:29], v[28:29]
	v_cvt_pk_bf16_f32 v26, v30, v31
	v_add_co_u32_e32 v30, vcc, s15, v140
	v_cvt_pk_bf16_f32 v27, v32, v33
	v_cvt_pk_bf16_f32 v28, v36, v37
	v_cvt_pk_bf16_f32 v29, v38, v39
	v_addc_co_u32_e32 v31, vcc, 0, v141, vcc
	v_max_f32_e32 v18, 0, v18
	v_max_f32_e32 v19, 0, v19
	global_store_dwordx4 v[30:31], v[26:29], off
	s_nop 1
	v_pk_mul_f32 v[26:27], v[18:19], v[18:19]
	v_max_f32_e32 v20, 0, v20
	v_max_f32_e32 v22, 0, v22
	v_max_f32_e32 v23, 0, v23
	v_max_f32_e32 v18, 0, v24
	v_max_f32_e32 v19, 0, v25
	v_max_f32_e32 v21, 0, v21
	s_mov_b64 s[20:21], 0x280000
	v_pk_mul_f32 v[22:23], v[22:23], v[22:23]
	v_pk_mul_f32 v[24:25], v[18:19], v[18:19]
	v_pk_mul_f32 v[28:29], v[20:21], v[20:21]
	v_lshl_add_u64 v[34:35], v[140:141], 0, s[20:21]
	v_cvt_pk_bf16_f32 v18, v22, v23
	v_cvt_pk_bf16_f32 v19, v24, v25
	v_cvt_pk_bf16_f32 v20, v26, v27
	v_cvt_pk_bf16_f32 v21, v28, v29
	v_max_f32_e32 v10, 0, v10
	v_max_f32_e32 v11, 0, v11
	global_store_dwordx4 v[34:35], v[18:21], off offset:256
	s_nop 1
	v_pk_mul_f32 v[20:21], v[10:11], v[10:11]
	v_max_f32_e32 v14, 0, v14
	v_max_f32_e32 v15, 0, v15
	v_max_f32_e32 v12, 0, v12
	v_pk_mul_f32 v[14:15], v[14:15], v[14:15]
	v_max_f32_e32 v10, 0, v16
	v_max_f32_e32 v11, 0, v17
	v_max_f32_e32 v13, 0, v13
	s_mov_b32 s15, 0x2c0000
	v_pk_mul_f32 v[16:17], v[10:11], v[10:11]
	v_pk_mul_f32 v[22:23], v[12:13], v[12:13]
	v_cvt_pk_bf16_f32 v10, v14, v15
	v_add_co_u32_e32 v14, vcc, s15, v140
	v_cvt_pk_bf16_f32 v11, v16, v17
	v_cvt_pk_bf16_f32 v12, v20, v21
	v_cvt_pk_bf16_f32 v13, v22, v23
	v_addc_co_u32_e32 v15, vcc, 0, v141, vcc
	v_max_f32_e32 v2, 0, v2
	v_max_f32_e32 v3, 0, v3
	global_store_dwordx4 v[14:15], v[10:13], off
	s_nop 1
	v_pk_mul_f32 v[10:11], v[2:3], v[2:3]
	v_max_f32_e32 v4, 0, v4
	v_max_f32_e32 v6, 0, v6
	v_max_f32_e32 v7, 0, v7
	v_max_f32_e32 v2, 0, v8
	v_max_f32_e32 v3, 0, v9
	v_max_f32_e32 v5, 0, v5
	s_mov_b64 s[20:21], 0x2c0000
	v_pk_mul_f32 v[6:7], v[6:7], v[6:7]
	v_pk_mul_f32 v[8:9], v[2:3], v[2:3]
	v_pk_mul_f32 v[12:13], v[4:5], v[4:5]
	v_lshl_add_u64 v[18:19], v[140:141], 0, s[20:21]
	v_cvt_pk_bf16_f32 v2, v6, v7
	v_cvt_pk_bf16_f32 v3, v8, v9
	v_cvt_pk_bf16_f32 v4, v10, v11
	v_cvt_pk_bf16_f32 v5, v12, v13
	s_andn2_b64 vcc, exec, s[40:41]
	s_mov_b64 s[20:21], -1
	global_store_dwordx4 v[18:19], v[2:5], off offset:256
	s_nop 1
	s_cbranch_vccnz .LBB0_26
	s_andn2_b64 vcc, exec, s[8:9]
	s_cbranch_vccnz .LBB0_25
	s_barrier
	s_branch .LBB0_25
